# v29 + map0's last 4 PV MFMAs of each step carried across the barrier and issued first thing in the next step (covers post-barrier LDS latency)
# baseline (speedup 1.0000x reference)
.LBB0_298:
	s_and_b64 vcc, exec, s[38:39]
	s_cbranch_vccz .Lat_hd_e
	s_cmp_eq_u32 s0, 4
	s_cbranch_scc1 .Lat_hd_e
	v_mfma_f32_32x32x16_bf16 v[32:47], v[2:5], v[120:123], v[32:47]
	v_mfma_f32_32x32x16_bf16 v[32:47], v[6:9], v[124:127], v[32:47]
	v_mfma_f32_32x32x16_bf16 v[16:31], v[240:243], v[120:123], v[16:31]
	v_mfma_f32_32x32x16_bf16 v[16:31], v[244:247], v[124:127], v[16:31]

.LBB0_300:
	v_add_u32_e32 v238, s10, v234
	ds_read_b64_tr_b16 v[176:177], v238
	ds_read_b64_tr_b16 v[178:179], v238 offset:512
	ds_read_b64_tr_b16 v[180:181], v238 offset:1024
	ds_read_b64_tr_b16 v[182:183], v238 offset:1536
	ds_read_b128 v[112:115], v229 offset:16384
	ds_read_b128 v[128:131], v229 offset:20480
	ds_read_b128 v[240:243], v230 offset:16384
	ds_read_b128 v[244:247], v230 offset:20480
	ds_read_b128 v[248:251], v231 offset:16384
	v_exp_f32_e32 v80, v80
	v_exp_f32_e32 v81, v81
	v_exp_f32_e32 v82, v82
	v_add_f32_e32 v0, 0, v80
	v_exp_f32_e32 v83, v83
	v_add_f32_e32 v0, v81, v0
	v_exp_f32_e32 v84, v84
	v_add_f32_e32 v0, v82, v0
	s_waitcnt lgkmcnt(4)
	v_mfma_f32_32x32x16_bf16 v[112:127], v[112:115], v[160:163], 0
	v_exp_f32_e32 v85, v85
	v_add_f32_e32 v0, v83, v0
	v_exp_f32_e32 v86, v86
	v_add_f32_e32 v0, v84, v0
	s_waitcnt lgkmcnt(3)
	v_mfma_f32_32x32x16_bf16 v[128:143], v[128:131], v[160:163], 0
	v_exp_f32_e32 v87, v87
	v_add_f32_e32 v0, v85, v0
	v_exp_f32_e32 v88, v88
	v_add_f32_e32 v0, v86, v0
	s_waitcnt lgkmcnt(2)
	v_mfma_f32_32x32x16_bf16 v[112:127], v[240:243], v[164:167], v[112:127]
	ds_read_b128 v[240:243], v231 offset:20480
	v_exp_f32_e32 v89, v89
	v_add_f32_e32 v0, v87, v0
	v_exp_f32_e32 v90, v90
	v_add_f32_e32 v0, v88, v0
	s_waitcnt lgkmcnt(2)
	v_mfma_f32_32x32x16_bf16 v[128:143], v[244:247], v[164:167], v[128:143]
	ds_read_b128 v[244:247], v232 offset:16384
	v_exp_f32_e32 v91, v91
	v_add_f32_e32 v0, v89, v0
	v_exp_f32_e32 v92, v92
	v_add_f32_e32 v0, v90, v0
	s_waitcnt lgkmcnt(2)
	v_mfma_f32_32x32x16_bf16 v[112:127], v[248:251], v[168:171], v[112:127]
	ds_read_b128 v[248:251], v232 offset:20480
	v_exp_f32_e32 v93, v93
	v_add_f32_e32 v0, v91, v0
	v_exp_f32_e32 v94, v94
	v_add_f32_e32 v0, v92, v0
	s_waitcnt lgkmcnt(2)
	v_mfma_f32_32x32x16_bf16 v[128:143], v[240:243], v[168:171], v[128:143]
	v_exp_f32_e32 v95, v95
	v_add_f32_e32 v0, v93, v0
	v_add_f32_e32 v0, v94, v0
	v_add_f32_e32 v0, v95, v0
	s_waitcnt lgkmcnt(1)
	v_mfma_f32_32x32x16_bf16 v[112:127], v[244:247], v[172:175], v[112:127]
	v_cvt_pk_bf16_f32 v188, v80, v81
	v_cvt_pk_bf16_f32 v189, v82, v83
	v_cvt_pk_bf16_f32 v190, v84, v85
	v_cvt_pk_bf16_f32 v191, v86, v87
	s_waitcnt lgkmcnt(0)
	v_mfma_f32_32x32x16_bf16 v[128:143], v[248:251], v[172:175], v[128:143]
	v_cvt_pk_bf16_f32 v192, v88, v89
	v_cvt_pk_bf16_f32 v193, v90, v91
	v_cvt_pk_bf16_f32 v194, v92, v93
	v_cvt_pk_bf16_f32 v195, v94, v95
	ds_read_b64_tr_b16 v[240:241], v238 offset:4096
	ds_read_b64_tr_b16 v[242:243], v238 offset:4608
	ds_read_b64_tr_b16 v[244:245], v238 offset:5120
	ds_read_b64_tr_b16 v[246:247], v238 offset:5632
	s_waitcnt lgkmcnt(6)
	v_mfma_f32_32x32x16_bf16 v[64:79], v[176:179], v[188:191], v[64:79]
	v_exp_f32_e32 v96, v96
	v_exp_f32_e32 v97, v97
	v_exp_f32_e32 v98, v98
	v_add_f32_e32 v0, v96, v0
	v_exp_f32_e32 v99, v99
	s_waitcnt lgkmcnt(4)
	v_mfma_f32_32x32x16_bf16 v[64:79], v[180:183], v[192:195], v[64:79]
	ds_read_b64_tr_b16 v[80:81], v238 offset:8192
	ds_read_b64_tr_b16 v[82:83], v238 offset:8704
	ds_read_b64_tr_b16 v[84:85], v238 offset:9216
	ds_read_b64_tr_b16 v[86:87], v238 offset:9728
	v_add_f32_e32 v0, v97, v0
	v_exp_f32_e32 v100, v100
	v_add_f32_e32 v0, v98, v0
	v_exp_f32_e32 v101, v101
	v_add_f32_e32 v0, v99, v0
	s_waitcnt lgkmcnt(6)
	v_mfma_f32_32x32x16_bf16 v[48:63], v[240:243], v[188:191], v[48:63]
	v_exp_f32_e32 v102, v102
	v_add_f32_e32 v0, v100, v0
	v_exp_f32_e32 v103, v103
	v_add_f32_e32 v0, v101, v0
	v_exp_f32_e32 v104, v104
	s_waitcnt lgkmcnt(4)
	v_mfma_f32_32x32x16_bf16 v[48:63], v[244:247], v[192:195], v[48:63]
	ds_read_b64_tr_b16 v[176:177], v238 offset:12288
	ds_read_b64_tr_b16 v[178:179], v238 offset:12800
	ds_read_b64_tr_b16 v[180:181], v238 offset:13312
	ds_read_b64_tr_b16 v[182:183], v238 offset:13824
	v_add_f32_e32 v0, v102, v0
	v_exp_f32_e32 v105, v105
	v_add_f32_e32 v0, v103, v0
	v_exp_f32_e32 v106, v106
	v_add_f32_e32 v0, v104, v0
	s_waitcnt lgkmcnt(6)
	v_mfma_f32_32x32x16_bf16 v[32:47], v[80:83], v[188:191], v[32:47]
	v_exp_f32_e32 v107, v107
	v_add_f32_e32 v0, v105, v0
	v_exp_f32_e32 v108, v108
	v_add_f32_e32 v0, v106, v0
	v_exp_f32_e32 v109, v109
	s_waitcnt lgkmcnt(4)
	v_mfma_f32_32x32x16_bf16 v[32:47], v[84:87], v[192:195], v[32:47]
	ds_read_b64_tr_b16 v[240:241], v238 offset:2048
	ds_read_b64_tr_b16 v[242:243], v238 offset:2560
	ds_read_b64_tr_b16 v[244:245], v238 offset:3072
	ds_read_b64_tr_b16 v[246:247], v238 offset:3584
	v_add_f32_e32 v0, v107, v0
	v_exp_f32_e32 v110, v110
	v_add_f32_e32 v0, v108, v0
	v_exp_f32_e32 v111, v111
	v_add_f32_e32 v0, v109, v0
	s_waitcnt lgkmcnt(6)
	v_mfma_f32_32x32x16_bf16 v[16:31], v[176:179], v[188:191], v[16:31]
	v_add_f32_e32 v0, v110, v0
	v_add_f32_e32 v0, v111, v0
	v_cvt_pk_bf16_f32 v196, v96, v97
	v_cvt_pk_bf16_f32 v197, v98, v99
	v_cvt_pk_bf16_f32 v198, v100, v101
	s_waitcnt lgkmcnt(4)
	v_mfma_f32_32x32x16_bf16 v[16:31], v[180:183], v[192:195], v[16:31]
	ds_read_b64_tr_b16 v[80:81], v238 offset:6144
	ds_read_b64_tr_b16 v[82:83], v238 offset:6656
	ds_read_b64_tr_b16 v[84:85], v238 offset:7168
	ds_read_b64_tr_b16 v[86:87], v238 offset:7680
	v_cvt_pk_bf16_f32 v199, v102, v103
	v_cvt_pk_bf16_f32 v200, v104, v105
	v_cvt_pk_bf16_f32 v201, v106, v107
	v_cvt_pk_bf16_f32 v202, v108, v109
	v_cvt_pk_bf16_f32 v203, v110, v111
	s_nop 1
	s_waitcnt lgkmcnt(6)
	v_mfma_f32_32x32x16_bf16 v[64:79], v[240:243], v[196:199], v[64:79]
	s_waitcnt lgkmcnt(4)
	v_mfma_f32_32x32x16_bf16 v[64:79], v[244:247], v[200:203], v[64:79]
	ds_read_b64_tr_b16 v[176:177], v238 offset:10240
	ds_read_b64_tr_b16 v[178:179], v238 offset:10752
	ds_read_b64_tr_b16 v[180:181], v238 offset:11264
	ds_read_b64_tr_b16 v[182:183], v238 offset:11776
	s_waitcnt lgkmcnt(6)
	v_mfma_f32_32x32x16_bf16 v[48:63], v[80:83], v[196:199], v[48:63]
	s_waitcnt lgkmcnt(4)
	v_mfma_f32_32x32x16_bf16 v[48:63], v[84:87], v[200:203], v[48:63]
	ds_read_b64_tr_b16 v[240:241], v238 offset:14336
	ds_read_b64_tr_b16 v[242:243], v238 offset:14848
	ds_read_b64_tr_b16 v[244:245], v238 offset:15360
	ds_read_b64_tr_b16 v[246:247], v238 offset:15872
.LBB0_304:
	s_cmpk_lt_u32 s0, 0x82
	s_cselect_b64 s[10:11], -1, 0
	s_cmpk_gt_u32 s0, 0x81
	s_cselect_b64 s[34:35], -1, 0
	s_and_b64 vcc, exec, s[34:35]
	s_cbranch_vccnz .LBB0_306
.LBB0_306:
	s_add_i32 s57, s33, 0
	s_cmpk_gt_u32 s0, 0x7f
	s_waitcnt vmcnt(0) lgkmcnt(0)
	s_barrier
	s_and_b64 vcc, exec, s[38:39]
	s_cbranch_vccz .Lat_hd_o
	v_mfma_f32_32x32x16_bf16 v[32:47], v[176:179], v[196:199], v[32:47]
	v_mfma_f32_32x32x16_bf16 v[32:47], v[180:183], v[200:203], v[32:47]
	v_mfma_f32_32x32x16_bf16 v[16:31], v[240:243], v[196:199], v[16:31]
	v_mfma_f32_32x32x16_bf16 v[16:31], v[244:247], v[200:203], v[16:31]
.Lat_hd_o:
	s_cmpk_gt_u32 s0, 0x7f
	s_cbranch_scc1 .LBB0_320
	s_andn2_b64 vcc, exec, s[58:59]
	s_cbranch_vccnz .Lat_o_nokw1
	s_cmp_eq_u32 s0, 4
	s_cbranch_scc1 .Lat_o_kreg1
	s_add_i32 s101, s64, 0xffffffc0
	v_mad_i64_i32 v[10:11], s[40:41], s101, v222, v[212:213]
	v_lshl_add_u64 v[12:13], v[10:11], 0, v[158:159]
	v_lshl_add_u64 v[10:11], v[10:11], 0, v[156:157]
	s_lshr_b32 s101, s100, 16
	s_add_i32 m0, s101, 0x4000
	s_nop 0
	global_load_lds_dwordx4 v[10:11], off
	s_add_i32 m0, m0, 0x400
	s_nop 0
	global_load_lds_dwordx4 v[12:13], off
	s_branch .Lat_o_nokw1

.LBB0_323:
	v_add_u32_e32 v188, s57, v233
	ds_read_b64_tr_b16 v[2:3], v188
	ds_read_b64_tr_b16 v[4:5], v188 offset:512
	ds_read_b64_tr_b16 v[6:7], v188 offset:1024
	ds_read_b64_tr_b16 v[8:9], v188 offset:1536
	ds_read_b128 v[80:83], v229
	ds_read_b128 v[96:99], v229 offset:4096
	ds_read_b128 v[240:243], v230
	ds_read_b128 v[244:247], v230 offset:4096
	ds_read_b128 v[248:251], v231
	v_exp_f32_e32 v112, v112
	v_exp_f32_e32 v113, v113
	v_exp_f32_e32 v114, v114
	v_add_f32_e32 v239, 0, v112
	v_exp_f32_e32 v115, v115
	v_add_f32_e32 v239, v113, v239
	v_exp_f32_e32 v116, v116
	v_add_f32_e32 v239, v114, v239
	s_waitcnt lgkmcnt(4)
	v_mfma_f32_32x32x16_bf16 v[80:95], v[80:83], v[160:163], 0
	v_exp_f32_e32 v117, v117
	v_add_f32_e32 v239, v115, v239
	v_exp_f32_e32 v118, v118
	v_add_f32_e32 v239, v116, v239
	s_waitcnt lgkmcnt(3)
	v_mfma_f32_32x32x16_bf16 v[96:111], v[96:99], v[160:163], 0
	v_exp_f32_e32 v119, v119
	v_add_f32_e32 v239, v117, v239
	v_exp_f32_e32 v120, v120
	v_add_f32_e32 v239, v118, v239
	s_waitcnt lgkmcnt(2)
	v_mfma_f32_32x32x16_bf16 v[80:95], v[240:243], v[164:167], v[80:95]
	ds_read_b128 v[240:243], v231 offset:4096
	v_exp_f32_e32 v121, v121
	v_add_f32_e32 v239, v119, v239
	v_exp_f32_e32 v122, v122
	v_add_f32_e32 v239, v120, v239
	s_waitcnt lgkmcnt(2)
	v_mfma_f32_32x32x16_bf16 v[96:111], v[244:247], v[164:167], v[96:111]
	ds_read_b128 v[244:247], v232
	v_exp_f32_e32 v123, v123
	v_add_f32_e32 v239, v121, v239
	v_exp_f32_e32 v124, v124
	v_add_f32_e32 v239, v122, v239
	s_waitcnt lgkmcnt(2)
	v_mfma_f32_32x32x16_bf16 v[80:95], v[248:251], v[168:171], v[80:95]
	ds_read_b128 v[248:251], v232 offset:4096
	v_exp_f32_e32 v125, v125
	v_add_f32_e32 v239, v123, v239
	v_exp_f32_e32 v126, v126
	v_add_f32_e32 v239, v124, v239
	s_waitcnt lgkmcnt(2)
	v_mfma_f32_32x32x16_bf16 v[96:111], v[240:243], v[168:171], v[96:111]
	v_exp_f32_e32 v127, v127
	v_add_f32_e32 v239, v125, v239
	v_add_f32_e32 v239, v126, v239
	v_add_f32_e32 v239, v127, v239
	s_waitcnt lgkmcnt(1)
	v_mfma_f32_32x32x16_bf16 v[80:95], v[244:247], v[172:175], v[80:95]
	v_cvt_pk_bf16_f32 v112, v112, v113
	v_cvt_pk_bf16_f32 v113, v114, v115
	v_cvt_pk_bf16_f32 v114, v116, v117
	v_cvt_pk_bf16_f32 v115, v118, v119
	s_waitcnt lgkmcnt(0)
	v_mfma_f32_32x32x16_bf16 v[96:111], v[248:251], v[172:175], v[96:111]
	v_cvt_pk_bf16_f32 v116, v120, v121
	v_cvt_pk_bf16_f32 v117, v122, v123
	v_cvt_pk_bf16_f32 v118, v124, v125
	v_cvt_pk_bf16_f32 v119, v126, v127
	ds_read_b64_tr_b16 v[240:241], v188 offset:4096
	ds_read_b64_tr_b16 v[242:243], v188 offset:4608
	ds_read_b64_tr_b16 v[244:245], v188 offset:5120
	ds_read_b64_tr_b16 v[246:247], v188 offset:5632
	s_waitcnt lgkmcnt(6)
	v_mfma_f32_32x32x16_bf16 v[64:79], v[2:5], v[112:115], v[64:79]
	v_exp_f32_e32 v128, v128
	v_exp_f32_e32 v129, v129
	v_exp_f32_e32 v130, v130
	v_add_f32_e32 v239, v128, v239
	v_exp_f32_e32 v131, v131
	s_waitcnt lgkmcnt(4)
	v_mfma_f32_32x32x16_bf16 v[64:79], v[6:9], v[116:119], v[64:79]
	ds_read_b64_tr_b16 v[176:177], v188 offset:8192
	ds_read_b64_tr_b16 v[178:179], v188 offset:8704
	ds_read_b64_tr_b16 v[180:181], v188 offset:9216
	ds_read_b64_tr_b16 v[182:183], v188 offset:9728
	v_add_f32_e32 v239, v129, v239
	v_exp_f32_e32 v132, v132
	v_add_f32_e32 v239, v130, v239
	v_exp_f32_e32 v133, v133
	v_add_f32_e32 v239, v131, v239
	s_waitcnt lgkmcnt(6)
	v_mfma_f32_32x32x16_bf16 v[48:63], v[240:243], v[112:115], v[48:63]
	v_exp_f32_e32 v134, v134
	v_add_f32_e32 v239, v132, v239
	v_exp_f32_e32 v135, v135
	v_add_f32_e32 v239, v133, v239
	v_exp_f32_e32 v136, v136
	s_waitcnt lgkmcnt(4)
	v_mfma_f32_32x32x16_bf16 v[48:63], v[244:247], v[116:119], v[48:63]
	ds_read_b64_tr_b16 v[2:3], v188 offset:12288
	ds_read_b64_tr_b16 v[4:5], v188 offset:12800
	ds_read_b64_tr_b16 v[6:7], v188 offset:13312
	ds_read_b64_tr_b16 v[8:9], v188 offset:13824
	v_add_f32_e32 v239, v134, v239
	v_exp_f32_e32 v137, v137
	v_add_f32_e32 v239, v135, v239
	v_exp_f32_e32 v138, v138
	v_add_f32_e32 v239, v136, v239
	s_waitcnt lgkmcnt(6)
	v_mfma_f32_32x32x16_bf16 v[32:47], v[176:179], v[112:115], v[32:47]
	v_exp_f32_e32 v139, v139
	v_add_f32_e32 v239, v137, v239
	v_exp_f32_e32 v140, v140
	v_add_f32_e32 v239, v138, v239
	v_exp_f32_e32 v141, v141
	s_waitcnt lgkmcnt(4)
	v_mfma_f32_32x32x16_bf16 v[32:47], v[180:183], v[116:119], v[32:47]
	ds_read_b64_tr_b16 v[240:241], v188 offset:2048
	ds_read_b64_tr_b16 v[242:243], v188 offset:2560
	ds_read_b64_tr_b16 v[244:245], v188 offset:3072
	ds_read_b64_tr_b16 v[246:247], v188 offset:3584
	v_add_f32_e32 v239, v139, v239
	v_exp_f32_e32 v142, v142
	v_add_f32_e32 v239, v140, v239
	v_exp_f32_e32 v143, v143
	v_add_f32_e32 v239, v141, v239
	s_waitcnt lgkmcnt(6)
	v_mfma_f32_32x32x16_bf16 v[16:31], v[2:5], v[112:115], v[16:31]
	v_add_f32_e32 v239, v142, v239
	v_add_f32_e32 v239, v143, v239
	v_cvt_pk_bf16_f32 v120, v128, v129
	v_cvt_pk_bf16_f32 v121, v130, v131
	v_cvt_pk_bf16_f32 v122, v132, v133
	s_waitcnt lgkmcnt(4)
	v_mfma_f32_32x32x16_bf16 v[16:31], v[6:9], v[116:119], v[16:31]
	ds_read_b64_tr_b16 v[176:177], v188 offset:6144
	ds_read_b64_tr_b16 v[178:179], v188 offset:6656
	ds_read_b64_tr_b16 v[180:181], v188 offset:7168
	ds_read_b64_tr_b16 v[182:183], v188 offset:7680
	v_cvt_pk_bf16_f32 v123, v134, v135
	v_cvt_pk_bf16_f32 v124, v136, v137
	v_cvt_pk_bf16_f32 v125, v138, v139
	v_cvt_pk_bf16_f32 v126, v140, v141
	v_cvt_pk_bf16_f32 v127, v142, v143
	s_nop 1
	s_waitcnt lgkmcnt(6)
	v_mfma_f32_32x32x16_bf16 v[64:79], v[240:243], v[120:123], v[64:79]
	v_mov_b32_e32 v128, v239
	s_waitcnt lgkmcnt(4)
	v_mfma_f32_32x32x16_bf16 v[64:79], v[244:247], v[124:127], v[64:79]
	ds_read_b64_tr_b16 v[2:3], v188 offset:10240
	ds_read_b64_tr_b16 v[4:5], v188 offset:10752
	ds_read_b64_tr_b16 v[6:7], v188 offset:11264
	ds_read_b64_tr_b16 v[8:9], v188 offset:11776
	s_waitcnt lgkmcnt(6)
	v_mfma_f32_32x32x16_bf16 v[48:63], v[176:179], v[120:123], v[48:63]
	s_waitcnt lgkmcnt(4)
	v_mfma_f32_32x32x16_bf16 v[48:63], v[180:183], v[124:127], v[48:63]
	ds_read_b64_tr_b16 v[240:241], v188 offset:14336
	ds_read_b64_tr_b16 v[242:243], v188 offset:14848
	ds_read_b64_tr_b16 v[244:245], v188 offset:15360
	ds_read_b64_tr_b16 v[246:247], v188 offset:15872
	s_branch .LBB0_314
